# P0 transposes: fifth round taken off the GEMV and the S5-discretisation workgroups; 16 other workgroups take a sixth item per wave
# baseline (speedup 1.0000x reference)
; __device__ __forceinline__ void p0_prologue(const Args& A, char* lds, int vcu, int G) {
;     ...
;     for (int it = gw; it < NITEMS; it += NGW) {
;         int r = it;
;         if (r < I0) { transpose_item<0>(A.in[I_EINW], 1024, 6672, NP0, (bf16*)(ws + WS_WT0), scr, r, lane); continue; } r -= I0;
;         if (r < I1) { transpose_item<1>(A.in[I_OINW], 1024, 7192, NP1, (bf16*)(ws + WS_WT1), scr, r, lane); continue; } r -= I1;
;         if (r < IO) { transpose_item<2>(A.in[I_EOUTW], 2048, 1024, 1024, (bf16*)(ws + WS_WO0), scr, r, lane, G == 256 ? A.in[I_ENORMG] : nullptr); continue; } r -= IO;
;         if (r < IO) { transpose_item<2>(A.in[I_OOUTW], 2048, 1024, 1024, (bf16*)(ws + WS_WO1), scr, r, lane); continue; } r -= IO;
;         transpose_item<2>(A.in[I_OGLUW], 512, 512, 512, (bf16*)(ws + WS_WG), scr, r, lane);
;     }
.LBB0_33:
	s_or_b64 exec, exec, s[52:53]
	v_add_u32_e32 v18, s44, v18
	v_lshrrev_b32_e32 v180, 11, v18
	v_subrev_u32_e32 v181, 0x2000, v18
	v_lshrrev_b32_e32 v182, 3, v181
	v_and_b32_e32 v183, 31, v182
	v_lshrrev_b32_e32 v182, 5, v182
	v_and_b32_e32 v181, 7, v181
	v_lshl_add_u32 v181, v182, 3, v181
	v_subrev_u32_e32 v182, 12, v183
	v_lshl_add_u32 v181, v182, 6, v181
	v_add_u32_e32 v181, 0x2000, v181
	v_cmp_lt_u32_e32 vcc, 15, v182
	v_mov_b32_e32 v182, 0x10000
	s_nop 1
	v_cndmask_b32_e32 v181, v181, v182, vcc
	v_cmp_eq_u32_e32 vcc, 4, v180
	v_lshrrev_b32_e32 v180, 7, v18
	v_subrev_u32_e32 v182, 0x400, v18
	v_cndmask_b32_e32 v181, v18, v181, vcc
	v_cmp_eq_u32_e32 vcc, 0x50, v180
	s_nop 1
	v_cndmask_b32_e32 v18, v181, v182, vcc
	v_cmp_lt_i32_e32 vcc, s94, v18
	s_or_b64 s[50:51], vcc, s[50:51]
	v_lshlrev_b32_e32 v27, 5, v18
	s_andn2_b64 exec, exec, s[50:51]
	s_cbranch_execz .LBB0_287
